# GEMM MMA segments reduced to barrier, 32 back-to-back MFMAs, barrier: priority flips outside, redundant lgkmcnt wait and mid-segment flip pair removed
# baseline (speedup 1.0000x reference)
.LBB0_176:
	s_add_u32 s2, s14, 0xfffc0080
	s_addc_u32 s3, s15, -1
	s_add_i32 s47, 0, 0x10000
	s_cmp_eq_u32 s46, 12
	s_cselect_b32 s25, s7, s3
	s_cselect_b32 s24, s11, s2
	v_add_u32_e32 v0, s47, v155
	s_cselect_b32 s3, s13, s33
	s_cselect_b32 s2, s29, s31
	s_add_i32 s54, 0, 0x14000
	ds_read_b128 v[50:53], v0
	ds_read_b128 v[54:57], v0 offset:1024
	ds_read_b128 v[58:61], v0 offset:2048
	ds_read_b128 v[62:65], v0 offset:3072
	v_add_u32_e32 v0, s54, v155
	ds_read_b128 v[176:179], v0
	ds_read_b128 v[188:191], v0 offset:1024
	ds_read_b128 v[192:195], v0 offset:2048
	ds_read_b128 v[196:199], v0 offset:3072
	v_lshl_add_u64 v[180:181], s[14:15], 0, v[170:171]
	s_add_i32 m0, s90, 0xc000
	ds_read_b128 v[200:203], v186
	ds_read_b128 v[204:207], v186 offset:1024
	ds_read_b128 v[226:229], v186 offset:2048
	ds_read_b128 v[230:233], v186 offset:3072
	ds_read_b128 v[234:237], v186 offset:4096
	ds_read_b128 v[238:241], v186 offset:5120
	ds_read_b128 v[242:245], v186 offset:6144
	ds_read_b128 v[246:249], v186 offset:7168
	global_load_lds_dwordx4 v[180:181], off
	v_lshl_add_u64 v[180:181], s[14:15], 0, v[172:173]
	s_add_i32 m0, s90, 0xe000
	s_nop 0
	global_load_lds_dwordx4 v[180:181], off
	s_waitcnt vmcnt(8)
	s_waitcnt lgkmcnt(0)
	s_setprio 1
	s_barrier
	v_mfma_f32_16x16x32_bf16 v[142:145], v[50:53], v[200:203], v[142:145]
	v_mfma_f32_16x16x32_bf16 v[138:141], v[58:61], v[200:203], v[138:141]
	v_mfma_f32_16x16x32_bf16 v[126:129], v[50:53], v[226:229], v[126:129]
	v_mfma_f32_16x16x32_bf16 v[122:125], v[58:61], v[226:229], v[122:125]
	v_mfma_f32_16x16x32_bf16 v[110:113], v[50:53], v[234:237], v[110:113]
	v_mfma_f32_16x16x32_bf16 v[106:109], v[58:61], v[234:237], v[106:109]
	v_mfma_f32_16x16x32_bf16 v[94:97], v[50:53], v[242:245], v[94:97]
	v_mfma_f32_16x16x32_bf16 v[90:93], v[58:61], v[242:245], v[90:93]
	v_mfma_f32_16x16x32_bf16 v[142:145], v[54:57], v[204:207], v[142:145]
	v_mfma_f32_16x16x32_bf16 v[138:141], v[62:65], v[204:207], v[138:141]
	v_mfma_f32_16x16x32_bf16 v[126:129], v[54:57], v[230:233], v[126:129]
	v_mfma_f32_16x16x32_bf16 v[122:125], v[62:65], v[230:233], v[122:125]
	v_mfma_f32_16x16x32_bf16 v[110:113], v[54:57], v[238:241], v[110:113]
	v_mfma_f32_16x16x32_bf16 v[106:109], v[62:65], v[238:241], v[106:109]
	v_mfma_f32_16x16x32_bf16 v[94:97], v[54:57], v[246:249], v[94:97]
	v_mfma_f32_16x16x32_bf16 v[90:93], v[62:65], v[246:249], v[90:93]
	v_mfma_f32_16x16x32_bf16 v[134:137], v[176:179], v[200:203], v[134:137]
	v_mfma_f32_16x16x32_bf16 v[130:133], v[192:195], v[200:203], v[130:133]
	v_mfma_f32_16x16x32_bf16 v[118:121], v[176:179], v[226:229], v[118:121]
	v_mfma_f32_16x16x32_bf16 v[114:117], v[192:195], v[226:229], v[114:117]
	v_mfma_f32_16x16x32_bf16 v[102:105], v[176:179], v[234:237], v[102:105]
	v_mfma_f32_16x16x32_bf16 v[98:101], v[192:195], v[234:237], v[98:101]
	v_mfma_f32_16x16x32_bf16 v[86:89], v[176:179], v[242:245], v[86:89]
	v_mfma_f32_16x16x32_bf16 v[82:85], v[192:195], v[242:245], v[82:85]
	v_mfma_f32_16x16x32_bf16 v[134:137], v[188:191], v[204:207], v[134:137]
	v_mfma_f32_16x16x32_bf16 v[130:133], v[196:199], v[204:207], v[130:133]
	v_mfma_f32_16x16x32_bf16 v[118:121], v[188:191], v[230:233], v[118:121]
	v_mfma_f32_16x16x32_bf16 v[114:117], v[196:199], v[230:233], v[114:117]
	v_mfma_f32_16x16x32_bf16 v[102:105], v[188:191], v[238:241], v[102:105]
	v_mfma_f32_16x16x32_bf16 v[98:101], v[196:199], v[238:241], v[98:101]
	v_mfma_f32_16x16x32_bf16 v[86:89], v[188:191], v[246:249], v[86:89]
	v_mfma_f32_16x16x32_bf16 v[82:85], v[196:199], v[246:249], v[82:85]
	s_barrier
	s_setprio 0
	s_add_i32 s47, s47, s42
	v_lshl_add_u64 v[180:181], s[2:3], 0, v[146:147]
	s_mov_b32 m0, s47
	ds_read_b128 v[200:203], v186 offset:16384
	ds_read_b128 v[204:207], v186 offset:17408
	ds_read_b128 v[226:229], v186 offset:18432
	ds_read_b128 v[230:233], v186 offset:19456
	ds_read_b128 v[234:237], v186 offset:20480
	ds_read_b128 v[238:241], v186 offset:21504
	ds_read_b128 v[242:245], v186 offset:22528
	ds_read_b128 v[246:249], v186 offset:23552
	global_load_lds_dwordx4 v[180:181], off
	s_add_i32 m0, s47, 0x2000
	s_add_u32 s58, s2, 0x40000
	v_lshl_add_u64 v[222:223], s[2:3], 0, v[148:149]
	s_addc_u32 s59, s3, 0
	s_add_i32 s47, s54, s42
	global_load_lds_dwordx4 v[222:223], off
	v_lshl_add_u64 v[224:225], s[58:59], 0, v[146:147]
	s_mov_b32 m0, s47
	v_lshl_add_u64 v[250:251], s[24:25], 0, v[148:149]
	global_load_lds_dwordx4 v[224:225], off
	v_lshl_add_u64 v[224:225], s[58:59], 0, v[148:149]
	s_add_i32 m0, s47, 0x2000
	s_nop 0
	global_load_lds_dwordx4 v[224:225], off
	v_lshl_add_u64 v[224:225], s[24:25], 0, v[146:147]
	s_mov_b32 m0, s90
	s_nop 0
	global_load_lds_dwordx4 v[224:225], off
	s_mov_b32 m0, s91
	s_nop 0
	global_load_lds_dwordx4 v[250:251], off
	s_waitcnt vmcnt(8)
	s_waitcnt lgkmcnt(0)
	s_setprio 1
	s_barrier
	v_mfma_f32_16x16x32_bf16 v[78:81], v[50:53], v[200:203], v[78:81]
	v_mfma_f32_16x16x32_bf16 v[74:77], v[58:61], v[200:203], v[74:77]
	v_mfma_f32_16x16x32_bf16 v[46:49], v[50:53], v[226:229], v[46:49]
	v_mfma_f32_16x16x32_bf16 v[42:45], v[58:61], v[226:229], v[42:45]
	v_mfma_f32_16x16x32_bf16 v[30:33], v[50:53], v[234:237], v[30:33]
	v_mfma_f32_16x16x32_bf16 v[26:29], v[58:61], v[234:237], v[26:29]
	v_mfma_f32_16x16x32_bf16 v[14:17], v[50:53], v[242:245], v[14:17]
	v_mfma_f32_16x16x32_bf16 v[10:13], v[58:61], v[242:245], v[10:13]
	v_mfma_f32_16x16x32_bf16 v[78:81], v[54:57], v[204:207], v[78:81]
	v_mfma_f32_16x16x32_bf16 v[74:77], v[62:65], v[204:207], v[74:77]
	v_mfma_f32_16x16x32_bf16 v[46:49], v[54:57], v[230:233], v[46:49]
	v_mfma_f32_16x16x32_bf16 v[42:45], v[62:65], v[230:233], v[42:45]
	v_mfma_f32_16x16x32_bf16 v[30:33], v[54:57], v[238:241], v[30:33]
	v_mfma_f32_16x16x32_bf16 v[26:29], v[62:65], v[238:241], v[26:29]
	v_mfma_f32_16x16x32_bf16 v[14:17], v[54:57], v[246:249], v[14:17]
	v_mfma_f32_16x16x32_bf16 v[10:13], v[62:65], v[246:249], v[10:13]
	v_mfma_f32_16x16x32_bf16 v[38:41], v[176:179], v[226:229], v[38:41]
	v_mfma_f32_16x16x32_bf16 v[34:37], v[192:195], v[226:229], v[34:37]
	v_mfma_f32_16x16x32_bf16 v[22:25], v[176:179], v[234:237], v[22:25]
	v_mfma_f32_16x16x32_bf16 v[18:21], v[192:195], v[234:237], v[18:21]
	v_mfma_f32_16x16x32_bf16 v[6:9], v[176:179], v[242:245], v[6:9]
	v_mfma_f32_16x16x32_bf16 v[2:5], v[192:195], v[242:245], v[2:5]
	v_mfma_f32_16x16x32_bf16 v[50:53], v[176:179], v[200:203], v[70:73]
	v_mfma_f32_16x16x32_bf16 v[54:57], v[192:195], v[200:203], v[66:69]
	v_mfma_f32_16x16x32_bf16 v[38:41], v[188:191], v[230:233], v[38:41]
	v_mfma_f32_16x16x32_bf16 v[34:37], v[196:199], v[230:233], v[34:37]
	v_mfma_f32_16x16x32_bf16 v[22:25], v[188:191], v[238:241], v[22:25]
	v_mfma_f32_16x16x32_bf16 v[18:21], v[196:199], v[238:241], v[18:21]
	v_mfma_f32_16x16x32_bf16 v[6:9], v[188:191], v[246:249], v[6:9]
	v_mfma_f32_16x16x32_bf16 v[2:5], v[196:199], v[246:249], v[2:5]
	v_mfma_f32_16x16x32_bf16 v[50:53], v[188:191], v[204:207], v[50:53]
	v_mfma_f32_16x16x32_bf16 v[54:57], v[196:199], v[204:207], v[54:57]
	s_barrier
	s_setprio 0
	s_add_i32 s47, 0, 0x18000
	v_add_u32_e32 v0, s47, v155
	s_add_i32 s54, 0, 0x1c000
	ds_read_b128 v[58:61], v0
	ds_read_b128 v[62:65], v0 offset:1024
	ds_read_b128 v[66:69], v0 offset:2048
	ds_read_b128 v[70:73], v0 offset:3072
	v_add_u32_e32 v0, s54, v155
	ds_read_b128 v[176:179], v0
	ds_read_b128 v[188:191], v0 offset:1024
	ds_read_b128 v[192:195], v0 offset:2048
	ds_read_b128 v[196:199], v0 offset:3072
	s_add_u32 s24, s24, 0x40000
	s_addc_u32 s25, s25, 0
	s_mov_b32 m0, s74
	v_lshl_add_u64 v[218:219], s[24:25], 0, v[146:147]
	ds_read_b128 v[200:203], v186 offset:32768
	ds_read_b128 v[204:207], v186 offset:33792
	ds_read_b128 v[226:229], v186 offset:34816
	ds_read_b128 v[230:233], v186 offset:35840
	ds_read_b128 v[234:237], v186 offset:36864
	ds_read_b128 v[238:241], v186 offset:37888
	ds_read_b128 v[242:245], v186 offset:38912
	ds_read_b128 v[246:249], v186 offset:39936
	global_load_lds_dwordx4 v[218:219], off
	v_lshl_add_u64 v[218:219], s[24:25], 0, v[148:149]
	s_mov_b32 m0, s75
	s_nop 0
	global_load_lds_dwordx4 v[218:219], off
	s_waitcnt vmcnt(8)
	s_waitcnt lgkmcnt(0)
	s_setprio 1
	s_barrier
	v_mfma_f32_16x16x32_bf16 v[142:145], v[58:61], v[200:203], v[142:145]
	v_mfma_f32_16x16x32_bf16 v[138:141], v[66:69], v[200:203], v[138:141]
	v_mfma_f32_16x16x32_bf16 v[126:129], v[58:61], v[226:229], v[126:129]
	v_mfma_f32_16x16x32_bf16 v[122:125], v[66:69], v[226:229], v[122:125]
	v_mfma_f32_16x16x32_bf16 v[110:113], v[58:61], v[234:237], v[110:113]
	v_mfma_f32_16x16x32_bf16 v[106:109], v[66:69], v[234:237], v[106:109]
	v_mfma_f32_16x16x32_bf16 v[94:97], v[58:61], v[242:245], v[94:97]
	v_mfma_f32_16x16x32_bf16 v[90:93], v[66:69], v[242:245], v[90:93]
	v_mfma_f32_16x16x32_bf16 v[142:145], v[62:65], v[204:207], v[142:145]
	v_mfma_f32_16x16x32_bf16 v[138:141], v[70:73], v[204:207], v[138:141]
	v_mfma_f32_16x16x32_bf16 v[126:129], v[62:65], v[230:233], v[126:129]
	v_mfma_f32_16x16x32_bf16 v[122:125], v[70:73], v[230:233], v[122:125]
	v_mfma_f32_16x16x32_bf16 v[110:113], v[62:65], v[238:241], v[110:113]
	v_mfma_f32_16x16x32_bf16 v[106:109], v[70:73], v[238:241], v[106:109]
	v_mfma_f32_16x16x32_bf16 v[94:97], v[62:65], v[246:249], v[94:97]
	v_mfma_f32_16x16x32_bf16 v[90:93], v[70:73], v[246:249], v[90:93]
	v_mfma_f32_16x16x32_bf16 v[134:137], v[176:179], v[200:203], v[134:137]
	v_mfma_f32_16x16x32_bf16 v[130:133], v[192:195], v[200:203], v[130:133]
	v_mfma_f32_16x16x32_bf16 v[118:121], v[176:179], v[226:229], v[118:121]
	v_mfma_f32_16x16x32_bf16 v[114:117], v[192:195], v[226:229], v[114:117]
	v_mfma_f32_16x16x32_bf16 v[102:105], v[176:179], v[234:237], v[102:105]
	v_mfma_f32_16x16x32_bf16 v[98:101], v[192:195], v[234:237], v[98:101]
	v_mfma_f32_16x16x32_bf16 v[86:89], v[176:179], v[242:245], v[86:89]
	v_mfma_f32_16x16x32_bf16 v[82:85], v[192:195], v[242:245], v[82:85]
	v_mfma_f32_16x16x32_bf16 v[134:137], v[188:191], v[204:207], v[134:137]
	v_mfma_f32_16x16x32_bf16 v[130:133], v[196:199], v[204:207], v[130:133]
	v_mfma_f32_16x16x32_bf16 v[118:121], v[188:191], v[230:233], v[118:121]
	v_mfma_f32_16x16x32_bf16 v[114:117], v[196:199], v[230:233], v[114:117]
	v_mfma_f32_16x16x32_bf16 v[102:105], v[188:191], v[238:241], v[102:105]
	v_mfma_f32_16x16x32_bf16 v[98:101], v[196:199], v[238:241], v[98:101]
	v_mfma_f32_16x16x32_bf16 v[86:89], v[188:191], v[246:249], v[86:89]
	v_mfma_f32_16x16x32_bf16 v[82:85], v[196:199], v[246:249], v[82:85]
	s_barrier
	s_setprio 0
	s_add_i32 s24, s47, s42
	v_lshl_add_u64 v[180:181], v[180:181], 0, s[44:45]
	s_mov_b32 m0, s24
	ds_read_b128 v[200:203], v186 offset:49152
	ds_read_b128 v[204:207], v186 offset:50176
	ds_read_b128 v[226:229], v186 offset:51200
	ds_read_b128 v[230:233], v186 offset:52224
	ds_read_b128 v[234:237], v186 offset:53248
	ds_read_b128 v[238:241], v186 offset:54272
	ds_read_b128 v[242:245], v186 offset:55296
	ds_read_b128 v[246:249], v186 offset:56320
	global_load_lds_dwordx4 v[180:181], off
	s_add_i32 m0, s24, 0x2000
	s_add_u32 s2, s2, 0x40080
	v_lshl_add_u64 v[180:181], v[222:223], 0, s[44:45]
	s_addc_u32 s3, s3, 0
	s_add_i32 s24, s54, s42
	global_load_lds_dwordx4 v[180:181], off
	v_lshl_add_u64 v[180:181], s[2:3], 0, v[146:147]
	s_mov_b32 m0, s24
	s_nop 0
	global_load_lds_dwordx4 v[180:181], off
	v_lshl_add_u64 v[180:181], s[2:3], 0, v[148:149]
	s_add_i32 m0, s24, 0x2000
	s_nop 0
	global_load_lds_dwordx4 v[180:181], off
	v_lshl_add_u64 v[180:181], v[224:225], 0, s[44:45]
	s_mov_b32 m0, s20
	s_nop 0
	global_load_lds_dwordx4 v[180:181], off
	v_lshl_add_u64 v[180:181], v[250:251], 0, s[44:45]
	s_mov_b32 m0, s21
	s_nop 0
	global_load_lds_dwordx4 v[180:181], off
	s_waitcnt vmcnt(8)
	s_waitcnt lgkmcnt(0)
	s_setprio 1
	s_barrier
	v_mfma_f32_16x16x32_bf16 v[78:81], v[58:61], v[200:203], v[78:81]
	v_mfma_f32_16x16x32_bf16 v[74:77], v[66:69], v[200:203], v[74:77]
	v_mfma_f32_16x16x32_bf16 v[46:49], v[58:61], v[226:229], v[46:49]
	v_mfma_f32_16x16x32_bf16 v[42:45], v[66:69], v[226:229], v[42:45]
	v_mfma_f32_16x16x32_bf16 v[30:33], v[58:61], v[234:237], v[30:33]
	v_mfma_f32_16x16x32_bf16 v[26:29], v[66:69], v[234:237], v[26:29]
	v_mfma_f32_16x16x32_bf16 v[14:17], v[58:61], v[242:245], v[14:17]
	v_mfma_f32_16x16x32_bf16 v[10:13], v[66:69], v[242:245], v[10:13]
	v_mfma_f32_16x16x32_bf16 v[78:81], v[62:65], v[204:207], v[78:81]
	v_mfma_f32_16x16x32_bf16 v[74:77], v[70:73], v[204:207], v[74:77]
	v_mfma_f32_16x16x32_bf16 v[46:49], v[62:65], v[230:233], v[46:49]
	v_mfma_f32_16x16x32_bf16 v[42:45], v[70:73], v[230:233], v[42:45]
	v_mfma_f32_16x16x32_bf16 v[30:33], v[62:65], v[238:241], v[30:33]
	v_mfma_f32_16x16x32_bf16 v[26:29], v[70:73], v[238:241], v[26:29]
	v_mfma_f32_16x16x32_bf16 v[14:17], v[62:65], v[246:249], v[14:17]
	v_mfma_f32_16x16x32_bf16 v[10:13], v[70:73], v[246:249], v[10:13]
	v_mfma_f32_16x16x32_bf16 v[50:53], v[176:179], v[200:203], v[50:53]
	v_mfma_f32_16x16x32_bf16 v[70:73], v[188:191], v[204:207], v[50:53]
	v_mfma_f32_16x16x32_bf16 v[50:53], v[192:195], v[200:203], v[54:57]
	v_mfma_f32_16x16x32_bf16 v[38:41], v[176:179], v[226:229], v[38:41]
	v_mfma_f32_16x16x32_bf16 v[34:37], v[192:195], v[226:229], v[34:37]
	v_mfma_f32_16x16x32_bf16 v[22:25], v[176:179], v[234:237], v[22:25]
	v_mfma_f32_16x16x32_bf16 v[18:21], v[192:195], v[234:237], v[18:21]
	v_mfma_f32_16x16x32_bf16 v[6:9], v[176:179], v[242:245], v[6:9]
	v_mfma_f32_16x16x32_bf16 v[2:5], v[192:195], v[242:245], v[2:5]
	v_mfma_f32_16x16x32_bf16 v[66:69], v[196:199], v[204:207], v[50:53]
	v_mfma_f32_16x16x32_bf16 v[38:41], v[188:191], v[230:233], v[38:41]
	v_mfma_f32_16x16x32_bf16 v[34:37], v[196:199], v[230:233], v[34:37]
	v_mfma_f32_16x16x32_bf16 v[22:25], v[188:191], v[238:241], v[22:25]
	v_mfma_f32_16x16x32_bf16 v[18:21], v[196:199], v[238:241], v[18:21]
	v_mfma_f32_16x16x32_bf16 v[6:9], v[188:191], v[246:249], v[6:9]
	v_mfma_f32_16x16x32_bf16 v[2:5], v[196:199], v[246:249], v[2:5]
	s_barrier
	s_setprio 0
	s_add_i32 s46, s46, 2
	s_add_u32 s14, s14, 0x100
	s_addc_u32 s15, s15, 0
	s_add_u32 s31, s31, 0x100
	s_addc_u32 s33, s33, 0
	s_cmp_gt_u32 s46, 13
	s_cbranch_scc0 .LBB0_176
	s_and_b64 vcc, exec, s[22:23]
	s_cbranch_vccz .LBB0_179
	s_barrier

.LBB0_650:
	s_add_u32 s2, s4, 0x100
	s_addc_u32 s3, s5, 0
	s_add_i32 s49, 0, 0x10000
	s_cmp_eq_u32 s48, 12
	s_cselect_b32 s29, s17, s3
	s_cselect_b32 s28, s25, s2
	v_add_u32_e32 v0, s49, v135
	s_cselect_b32 s27, s15, s47
	s_cselect_b32 s26, s42, s46
	s_add_i32 s50, 0, 0x14000
	ds_read_b128 v[146:149], v0
	ds_read_b128 v[150:153], v0 offset:1024
	ds_read_b128 v[154:157], v0 offset:2048
	ds_read_b128 v[158:161], v0 offset:3072
	v_add_u32_e32 v0, s50, v135
	ds_read_b128 v[162:165], v0
	ds_read_b128 v[166:169], v0 offset:1024
	ds_read_b128 v[170:173], v0 offset:2048
	ds_read_b128 v[174:177], v0 offset:3072
	v_lshl_add_u64 v[142:143], s[4:5], 0, v[138:139]
	s_add_i32 m0, s23, 0xc000
	ds_read_b128 v[178:181], v144
	ds_read_b128 v[182:185], v144 offset:1024
	ds_read_b128 v[186:189], v144 offset:2048
	ds_read_b128 v[190:193], v144 offset:3072
	ds_read_b128 v[194:197], v144 offset:4096
	ds_read_b128 v[198:201], v144 offset:5120
	ds_read_b128 v[202:205], v144 offset:6144
	ds_read_b128 v[222:225], v144 offset:7168
	global_load_lds_dwordx4 v[142:143], off
	v_lshl_add_u64 v[142:143], s[4:5], 0, v[140:141]
	s_add_i32 m0, s23, 0xe000
	s_nop 0
	global_load_lds_dwordx4 v[142:143], off
	s_waitcnt vmcnt(8)
	s_waitcnt lgkmcnt(0)
	s_setprio 1
	s_barrier
	v_mfma_f32_16x16x32_bf16 v[126:129], v[146:149], v[178:181], v[126:129]
	v_mfma_f32_16x16x32_bf16 v[122:125], v[154:157], v[178:181], v[122:125]
	v_mfma_f32_16x16x32_bf16 v[110:113], v[146:149], v[186:189], v[110:113]
	v_mfma_f32_16x16x32_bf16 v[106:109], v[154:157], v[186:189], v[106:109]
	v_mfma_f32_16x16x32_bf16 v[94:97], v[146:149], v[194:197], v[94:97]
	v_mfma_f32_16x16x32_bf16 v[90:93], v[154:157], v[194:197], v[90:93]
	v_mfma_f32_16x16x32_bf16 v[78:81], v[146:149], v[202:205], v[78:81]
	v_mfma_f32_16x16x32_bf16 v[74:77], v[154:157], v[202:205], v[74:77]
	v_mfma_f32_16x16x32_bf16 v[126:129], v[150:153], v[182:185], v[126:129]
	v_mfma_f32_16x16x32_bf16 v[122:125], v[158:161], v[182:185], v[122:125]
	v_mfma_f32_16x16x32_bf16 v[110:113], v[150:153], v[190:193], v[110:113]
	v_mfma_f32_16x16x32_bf16 v[106:109], v[158:161], v[190:193], v[106:109]
	v_mfma_f32_16x16x32_bf16 v[94:97], v[150:153], v[198:201], v[94:97]
	v_mfma_f32_16x16x32_bf16 v[90:93], v[158:161], v[198:201], v[90:93]
	v_mfma_f32_16x16x32_bf16 v[78:81], v[150:153], v[222:225], v[78:81]
	v_mfma_f32_16x16x32_bf16 v[74:77], v[158:161], v[222:225], v[74:77]
	v_mfma_f32_16x16x32_bf16 v[118:121], v[162:165], v[178:181], v[118:121]
	v_mfma_f32_16x16x32_bf16 v[114:117], v[170:173], v[178:181], v[114:117]
	v_mfma_f32_16x16x32_bf16 v[102:105], v[162:165], v[186:189], v[102:105]
	v_mfma_f32_16x16x32_bf16 v[98:101], v[170:173], v[186:189], v[98:101]
	v_mfma_f32_16x16x32_bf16 v[86:89], v[162:165], v[194:197], v[86:89]
	v_mfma_f32_16x16x32_bf16 v[82:85], v[170:173], v[194:197], v[82:85]
	v_mfma_f32_16x16x32_bf16 v[70:73], v[162:165], v[202:205], v[70:73]
	v_mfma_f32_16x16x32_bf16 v[66:69], v[170:173], v[202:205], v[66:69]
	v_mfma_f32_16x16x32_bf16 v[118:121], v[166:169], v[182:185], v[118:121]
	v_mfma_f32_16x16x32_bf16 v[114:117], v[174:177], v[182:185], v[114:117]
	v_mfma_f32_16x16x32_bf16 v[102:105], v[166:169], v[190:193], v[102:105]
	v_mfma_f32_16x16x32_bf16 v[98:101], v[174:177], v[190:193], v[98:101]
	v_mfma_f32_16x16x32_bf16 v[86:89], v[166:169], v[198:201], v[86:89]
	v_mfma_f32_16x16x32_bf16 v[82:85], v[174:177], v[198:201], v[82:85]
	v_mfma_f32_16x16x32_bf16 v[70:73], v[166:169], v[222:225], v[70:73]
	v_mfma_f32_16x16x32_bf16 v[66:69], v[174:177], v[222:225], v[66:69]
	s_barrier
	s_setprio 0
	s_add_i32 s4, s49, s30
	v_lshl_add_u64 v[142:143], s[26:27], 0, v[130:131]
	s_mov_b32 m0, s4
	ds_read_b128 v[178:181], v144 offset:16384
	ds_read_b128 v[182:185], v144 offset:17408
	ds_read_b128 v[186:189], v144 offset:18432
	ds_read_b128 v[190:193], v144 offset:19456
	ds_read_b128 v[194:197], v144 offset:20480
	ds_read_b128 v[198:201], v144 offset:21504
	ds_read_b128 v[202:205], v144 offset:22528
	ds_read_b128 v[222:225], v144 offset:23552
	global_load_lds_dwordx4 v[142:143], off
	s_add_i32 m0, s4, 0x2000
	s_add_u32 s4, s26, 0x40000
	v_lshl_add_u64 v[206:207], s[26:27], 0, v[132:133]
	s_addc_u32 s5, s27, 0
	s_add_i32 s49, s50, s30
	global_load_lds_dwordx4 v[206:207], off
	v_lshl_add_u64 v[218:219], s[4:5], 0, v[130:131]
	s_mov_b32 m0, s49
	v_lshl_add_u64 v[226:227], s[28:29], 0, v[132:133]
	global_load_lds_dwordx4 v[218:219], off
	v_lshl_add_u64 v[218:219], s[4:5], 0, v[132:133]
	s_add_i32 m0, s49, 0x2000
	s_nop 0
	global_load_lds_dwordx4 v[218:219], off
	v_lshl_add_u64 v[218:219], s[28:29], 0, v[130:131]
	s_mov_b32 m0, s23
	s_nop 0
	global_load_lds_dwordx4 v[218:219], off
	s_mov_b32 m0, s31
	s_nop 0
	global_load_lds_dwordx4 v[226:227], off
	s_waitcnt vmcnt(8)
	s_waitcnt lgkmcnt(0)
	s_setprio 1
	s_barrier
	v_mfma_f32_16x16x32_bf16 v[62:65], v[146:149], v[178:181], v[62:65]
	v_mfma_f32_16x16x32_bf16 v[58:61], v[154:157], v[178:181], v[58:61]
	v_mfma_f32_16x16x32_bf16 v[46:49], v[146:149], v[186:189], v[46:49]
	v_mfma_f32_16x16x32_bf16 v[42:45], v[154:157], v[186:189], v[42:45]
	v_mfma_f32_16x16x32_bf16 v[30:33], v[146:149], v[194:197], v[30:33]
	v_mfma_f32_16x16x32_bf16 v[26:29], v[154:157], v[194:197], v[26:29]
	v_mfma_f32_16x16x32_bf16 v[14:17], v[146:149], v[202:205], v[14:17]
	v_mfma_f32_16x16x32_bf16 v[10:13], v[154:157], v[202:205], v[10:13]
	v_mfma_f32_16x16x32_bf16 v[62:65], v[150:153], v[182:185], v[62:65]
	v_mfma_f32_16x16x32_bf16 v[58:61], v[158:161], v[182:185], v[58:61]
	v_mfma_f32_16x16x32_bf16 v[46:49], v[150:153], v[190:193], v[46:49]
	v_mfma_f32_16x16x32_bf16 v[42:45], v[158:161], v[190:193], v[42:45]
	v_mfma_f32_16x16x32_bf16 v[30:33], v[150:153], v[198:201], v[30:33]
	v_mfma_f32_16x16x32_bf16 v[26:29], v[158:161], v[198:201], v[26:29]
	v_mfma_f32_16x16x32_bf16 v[14:17], v[150:153], v[222:225], v[14:17]
	v_mfma_f32_16x16x32_bf16 v[10:13], v[158:161], v[222:225], v[10:13]
	v_mfma_f32_16x16x32_bf16 v[54:57], v[162:165], v[178:181], v[54:57]
	v_mfma_f32_16x16x32_bf16 v[50:53], v[170:173], v[178:181], v[50:53]
	v_mfma_f32_16x16x32_bf16 v[38:41], v[162:165], v[186:189], v[38:41]
	v_mfma_f32_16x16x32_bf16 v[34:37], v[170:173], v[186:189], v[34:37]
	v_mfma_f32_16x16x32_bf16 v[22:25], v[162:165], v[194:197], v[22:25]
	v_mfma_f32_16x16x32_bf16 v[18:21], v[170:173], v[194:197], v[18:21]
	v_mfma_f32_16x16x32_bf16 v[6:9], v[162:165], v[202:205], v[6:9]
	v_mfma_f32_16x16x32_bf16 v[2:5], v[170:173], v[202:205], v[2:5]
	v_mfma_f32_16x16x32_bf16 v[54:57], v[166:169], v[182:185], v[54:57]
	v_mfma_f32_16x16x32_bf16 v[50:53], v[174:177], v[182:185], v[50:53]
	v_mfma_f32_16x16x32_bf16 v[38:41], v[166:169], v[190:193], v[38:41]
	v_mfma_f32_16x16x32_bf16 v[34:37], v[174:177], v[190:193], v[34:37]
	v_mfma_f32_16x16x32_bf16 v[22:25], v[166:169], v[198:201], v[22:25]
	v_mfma_f32_16x16x32_bf16 v[18:21], v[174:177], v[198:201], v[18:21]
	v_mfma_f32_16x16x32_bf16 v[6:9], v[166:169], v[222:225], v[6:9]
	v_mfma_f32_16x16x32_bf16 v[2:5], v[174:177], v[222:225], v[2:5]
	s_barrier
	s_setprio 0
	s_add_i32 s49, 0, 0x18000
	v_add_u32_e32 v0, s49, v135
	s_add_i32 s50, 0, 0x1c000
	ds_read_b128 v[146:149], v0
	ds_read_b128 v[150:153], v0 offset:1024
	ds_read_b128 v[154:157], v0 offset:2048
	ds_read_b128 v[158:161], v0 offset:3072
	v_add_u32_e32 v0, s50, v135
	ds_read_b128 v[162:165], v0
	ds_read_b128 v[166:169], v0 offset:1024
	ds_read_b128 v[170:173], v0 offset:2048
	ds_read_b128 v[174:177], v0 offset:3072
	s_add_u32 s4, s28, 0x40000
	s_addc_u32 s5, s29, 0
	s_mov_b32 m0, s33
	v_lshl_add_u64 v[228:229], s[4:5], 0, v[130:131]
	ds_read_b128 v[178:181], v144 offset:32768
	ds_read_b128 v[182:185], v144 offset:33792
	ds_read_b128 v[186:189], v144 offset:34816
	ds_read_b128 v[190:193], v144 offset:35840
	ds_read_b128 v[194:197], v144 offset:36864
	ds_read_b128 v[198:201], v144 offset:37888
	ds_read_b128 v[202:205], v144 offset:38912
	ds_read_b128 v[222:225], v144 offset:39936
	global_load_lds_dwordx4 v[228:229], off
	v_lshl_add_u64 v[228:229], s[4:5], 0, v[132:133]
	s_mov_b32 m0, s34
	s_nop 0
	global_load_lds_dwordx4 v[228:229], off
	s_waitcnt vmcnt(8)
	s_waitcnt lgkmcnt(0)
	s_setprio 1
	s_barrier
	v_mfma_f32_16x16x32_bf16 v[126:129], v[146:149], v[178:181], v[126:129]
	v_mfma_f32_16x16x32_bf16 v[122:125], v[154:157], v[178:181], v[122:125]
	v_mfma_f32_16x16x32_bf16 v[110:113], v[146:149], v[186:189], v[110:113]
	v_mfma_f32_16x16x32_bf16 v[106:109], v[154:157], v[186:189], v[106:109]
	v_mfma_f32_16x16x32_bf16 v[94:97], v[146:149], v[194:197], v[94:97]
	v_mfma_f32_16x16x32_bf16 v[90:93], v[154:157], v[194:197], v[90:93]
	v_mfma_f32_16x16x32_bf16 v[78:81], v[146:149], v[202:205], v[78:81]
	v_mfma_f32_16x16x32_bf16 v[74:77], v[154:157], v[202:205], v[74:77]
	v_mfma_f32_16x16x32_bf16 v[126:129], v[150:153], v[182:185], v[126:129]
	v_mfma_f32_16x16x32_bf16 v[122:125], v[158:161], v[182:185], v[122:125]
	v_mfma_f32_16x16x32_bf16 v[110:113], v[150:153], v[190:193], v[110:113]
	v_mfma_f32_16x16x32_bf16 v[106:109], v[158:161], v[190:193], v[106:109]
	v_mfma_f32_16x16x32_bf16 v[94:97], v[150:153], v[198:201], v[94:97]
	v_mfma_f32_16x16x32_bf16 v[90:93], v[158:161], v[198:201], v[90:93]
	v_mfma_f32_16x16x32_bf16 v[78:81], v[150:153], v[222:225], v[78:81]
	v_mfma_f32_16x16x32_bf16 v[74:77], v[158:161], v[222:225], v[74:77]
	v_mfma_f32_16x16x32_bf16 v[118:121], v[162:165], v[178:181], v[118:121]
	v_mfma_f32_16x16x32_bf16 v[114:117], v[170:173], v[178:181], v[114:117]
	v_mfma_f32_16x16x32_bf16 v[102:105], v[162:165], v[186:189], v[102:105]
	v_mfma_f32_16x16x32_bf16 v[98:101], v[170:173], v[186:189], v[98:101]
	v_mfma_f32_16x16x32_bf16 v[86:89], v[162:165], v[194:197], v[86:89]
	v_mfma_f32_16x16x32_bf16 v[82:85], v[170:173], v[194:197], v[82:85]
	v_mfma_f32_16x16x32_bf16 v[70:73], v[162:165], v[202:205], v[70:73]
	v_mfma_f32_16x16x32_bf16 v[66:69], v[170:173], v[202:205], v[66:69]
	v_mfma_f32_16x16x32_bf16 v[118:121], v[166:169], v[182:185], v[118:121]
	v_mfma_f32_16x16x32_bf16 v[114:117], v[174:177], v[182:185], v[114:117]
	v_mfma_f32_16x16x32_bf16 v[102:105], v[166:169], v[190:193], v[102:105]
	v_mfma_f32_16x16x32_bf16 v[98:101], v[174:177], v[190:193], v[98:101]
	v_mfma_f32_16x16x32_bf16 v[86:89], v[166:169], v[198:201], v[86:89]
	v_mfma_f32_16x16x32_bf16 v[82:85], v[174:177], v[198:201], v[82:85]
	v_mfma_f32_16x16x32_bf16 v[70:73], v[166:169], v[222:225], v[70:73]
	v_mfma_f32_16x16x32_bf16 v[66:69], v[174:177], v[222:225], v[66:69]
	s_barrier
	s_setprio 0
	s_add_i32 s4, s49, s30
	v_lshl_add_u64 v[142:143], v[142:143], 0, s[44:45]
	s_mov_b32 m0, s4
	ds_read_b128 v[178:181], v144 offset:49152
	ds_read_b128 v[182:185], v144 offset:50176
	ds_read_b128 v[186:189], v144 offset:51200
	ds_read_b128 v[190:193], v144 offset:52224
	ds_read_b128 v[194:197], v144 offset:53248
	ds_read_b128 v[198:201], v144 offset:54272
	ds_read_b128 v[202:205], v144 offset:55296
	ds_read_b128 v[222:225], v144 offset:56320
	global_load_lds_dwordx4 v[142:143], off
	s_add_i32 m0, s4, 0x2000
	s_add_u32 s4, s26, 0x40080
	v_lshl_add_u64 v[142:143], v[206:207], 0, s[44:45]
	s_addc_u32 s5, s27, 0
	s_add_i32 s26, s50, s30
	global_load_lds_dwordx4 v[142:143], off
	v_lshl_add_u64 v[142:143], s[4:5], 0, v[130:131]
	s_mov_b32 m0, s26
	s_nop 0
	global_load_lds_dwordx4 v[142:143], off
	v_lshl_add_u64 v[142:143], s[4:5], 0, v[132:133]
	s_add_i32 m0, s26, 0x2000
	s_nop 0
	global_load_lds_dwordx4 v[142:143], off
	v_lshl_add_u64 v[142:143], v[218:219], 0, s[44:45]
	s_mov_b32 m0, s37
	s_nop 0
	global_load_lds_dwordx4 v[142:143], off
	v_lshl_add_u64 v[142:143], v[226:227], 0, s[44:45]
	s_mov_b32 m0, s38
	s_nop 0
	global_load_lds_dwordx4 v[142:143], off
	s_waitcnt vmcnt(8)
	s_waitcnt lgkmcnt(0)
	s_setprio 1
	s_barrier
	v_mfma_f32_16x16x32_bf16 v[62:65], v[146:149], v[178:181], v[62:65]
	v_mfma_f32_16x16x32_bf16 v[58:61], v[154:157], v[178:181], v[58:61]
	v_mfma_f32_16x16x32_bf16 v[46:49], v[146:149], v[186:189], v[46:49]
	v_mfma_f32_16x16x32_bf16 v[42:45], v[154:157], v[186:189], v[42:45]
	v_mfma_f32_16x16x32_bf16 v[30:33], v[146:149], v[194:197], v[30:33]
	v_mfma_f32_16x16x32_bf16 v[26:29], v[154:157], v[194:197], v[26:29]
	v_mfma_f32_16x16x32_bf16 v[14:17], v[146:149], v[202:205], v[14:17]
	v_mfma_f32_16x16x32_bf16 v[10:13], v[154:157], v[202:205], v[10:13]
	v_mfma_f32_16x16x32_bf16 v[62:65], v[150:153], v[182:185], v[62:65]
	v_mfma_f32_16x16x32_bf16 v[58:61], v[158:161], v[182:185], v[58:61]
	v_mfma_f32_16x16x32_bf16 v[46:49], v[150:153], v[190:193], v[46:49]
	v_mfma_f32_16x16x32_bf16 v[42:45], v[158:161], v[190:193], v[42:45]
	v_mfma_f32_16x16x32_bf16 v[30:33], v[150:153], v[198:201], v[30:33]
	v_mfma_f32_16x16x32_bf16 v[26:29], v[158:161], v[198:201], v[26:29]
	v_mfma_f32_16x16x32_bf16 v[14:17], v[150:153], v[222:225], v[14:17]
	v_mfma_f32_16x16x32_bf16 v[10:13], v[158:161], v[222:225], v[10:13]
	v_mfma_f32_16x16x32_bf16 v[54:57], v[162:165], v[178:181], v[54:57]
	v_mfma_f32_16x16x32_bf16 v[50:53], v[170:173], v[178:181], v[50:53]
	v_mfma_f32_16x16x32_bf16 v[38:41], v[162:165], v[186:189], v[38:41]
	v_mfma_f32_16x16x32_bf16 v[34:37], v[170:173], v[186:189], v[34:37]
	v_mfma_f32_16x16x32_bf16 v[22:25], v[162:165], v[194:197], v[22:25]
	v_mfma_f32_16x16x32_bf16 v[18:21], v[170:173], v[194:197], v[18:21]
	v_mfma_f32_16x16x32_bf16 v[6:9], v[162:165], v[202:205], v[6:9]
	v_mfma_f32_16x16x32_bf16 v[2:5], v[170:173], v[202:205], v[2:5]
	v_mfma_f32_16x16x32_bf16 v[54:57], v[166:169], v[182:185], v[54:57]
	v_mfma_f32_16x16x32_bf16 v[50:53], v[174:177], v[182:185], v[50:53]
	v_mfma_f32_16x16x32_bf16 v[38:41], v[166:169], v[190:193], v[38:41]
	v_mfma_f32_16x16x32_bf16 v[34:37], v[174:177], v[190:193], v[34:37]
	v_mfma_f32_16x16x32_bf16 v[22:25], v[166:169], v[198:201], v[22:25]
	v_mfma_f32_16x16x32_bf16 v[18:21], v[174:177], v[198:201], v[18:21]
	v_mfma_f32_16x16x32_bf16 v[6:9], v[166:169], v[222:225], v[6:9]
	v_mfma_f32_16x16x32_bf16 v[2:5], v[174:177], v[222:225], v[2:5]
	s_barrier
	s_setprio 0
	s_add_i32 s48, s48, 2
	s_add_u32 s46, s46, 0x100
	s_addc_u32 s47, s47, 0
	s_cmp_gt_u32 s48, 13
	s_mov_b64 s[4:5], s[2:3]
	s_cbranch_scc0 .LBB0_650
	s_and_b64 vcc, exec, s[12:13]
	s_cbranch_vccz .LBB0_653
	s_barrier

.LBB0_783:
	s_add_u32 s2, s4, 0xfffc0080
	s_addc_u32 s3, s5, -1
	s_add_i32 s48, 0, 0x10000
	s_cmp_eq_u32 s47, 12
	s_cselect_b32 s27, s17, s3
	s_cselect_b32 s26, s25, s2
	s_cselect_b32 s3, s15, s46
	s_cselect_b32 s2, s41, s42
	s_add_i32 s50, 0, 0x14000
	v_add_u32_e32 v154, s48, v140
	v_add_u32_e32 v170, s50, v140
	ds_read_b128 v[142:145], v154
	ds_read_b128 v[146:149], v154 offset:1024
	ds_read_b128 v[150:153], v154 offset:2048
	ds_read_b128 v[154:157], v154 offset:3072
	ds_read_b128 v[158:161], v170
	ds_read_b128 v[162:165], v170 offset:1024
	ds_read_b128 v[166:169], v170 offset:2048
	ds_read_b128 v[170:173], v170 offset:3072
	v_lshl_add_u64 v[206:207], s[4:5], 0, v[136:137]
	s_add_i32 m0, s23, 0xc000
	ds_read_b128 v[174:177], v141
	ds_read_b128 v[178:181], v141 offset:1024
	ds_read_b128 v[182:185], v141 offset:2048
	ds_read_b128 v[186:189], v141 offset:3072
	ds_read_b128 v[190:193], v141 offset:4096
	ds_read_b128 v[194:197], v141 offset:5120
	ds_read_b128 v[198:201], v141 offset:6144
	ds_read_b128 v[202:205], v141 offset:7168
	global_load_lds_dwordx4 v[206:207], off
	v_lshl_add_u64 v[206:207], s[4:5], 0, v[138:139]
	s_add_i32 m0, s23, 0xe000
	s_nop 0
	global_load_lds_dwordx4 v[206:207], off
	s_waitcnt vmcnt(8)
	s_waitcnt lgkmcnt(0)
	s_setprio 1
	s_barrier
	v_mfma_f32_16x16x32_bf16 v[122:125], v[142:145], v[174:177], v[122:125]
	v_mfma_f32_16x16x32_bf16 v[114:117], v[150:153], v[174:177], v[114:117]
	v_mfma_f32_16x16x32_bf16 v[106:109], v[142:145], v[182:185], v[106:109]
	v_mfma_f32_16x16x32_bf16 v[98:101], v[150:153], v[182:185], v[98:101]
	v_mfma_f32_16x16x32_bf16 v[90:93], v[142:145], v[190:193], v[90:93]
	v_mfma_f32_16x16x32_bf16 v[82:85], v[150:153], v[190:193], v[82:85]
	v_mfma_f32_16x16x32_bf16 v[74:77], v[142:145], v[198:201], v[74:77]
	v_mfma_f32_16x16x32_bf16 v[66:69], v[150:153], v[198:201], v[66:69]
	v_mfma_f32_16x16x32_bf16 v[122:125], v[146:149], v[178:181], v[122:125]
	v_mfma_f32_16x16x32_bf16 v[114:117], v[154:157], v[178:181], v[114:117]
	v_mfma_f32_16x16x32_bf16 v[106:109], v[146:149], v[186:189], v[106:109]
	v_mfma_f32_16x16x32_bf16 v[98:101], v[154:157], v[186:189], v[98:101]
	v_mfma_f32_16x16x32_bf16 v[90:93], v[146:149], v[194:197], v[90:93]
	v_mfma_f32_16x16x32_bf16 v[82:85], v[154:157], v[194:197], v[82:85]
	v_mfma_f32_16x16x32_bf16 v[74:77], v[146:149], v[202:205], v[74:77]
	v_mfma_f32_16x16x32_bf16 v[66:69], v[154:157], v[202:205], v[66:69]
	v_mfma_f32_16x16x32_bf16 v[126:129], v[158:161], v[174:177], v[126:129]
	v_mfma_f32_16x16x32_bf16 v[118:121], v[166:169], v[174:177], v[118:121]
	v_mfma_f32_16x16x32_bf16 v[110:113], v[158:161], v[182:185], v[110:113]
	v_mfma_f32_16x16x32_bf16 v[102:105], v[166:169], v[182:185], v[102:105]
	v_mfma_f32_16x16x32_bf16 v[94:97], v[158:161], v[190:193], v[94:97]
	v_mfma_f32_16x16x32_bf16 v[86:89], v[166:169], v[190:193], v[86:89]
	v_mfma_f32_16x16x32_bf16 v[78:81], v[158:161], v[198:201], v[78:81]
	v_mfma_f32_16x16x32_bf16 v[70:73], v[166:169], v[198:201], v[70:73]
	v_mfma_f32_16x16x32_bf16 v[126:129], v[162:165], v[178:181], v[126:129]
	v_mfma_f32_16x16x32_bf16 v[118:121], v[170:173], v[178:181], v[118:121]
	v_mfma_f32_16x16x32_bf16 v[110:113], v[162:165], v[186:189], v[110:113]
	v_mfma_f32_16x16x32_bf16 v[102:105], v[170:173], v[186:189], v[102:105]
	v_mfma_f32_16x16x32_bf16 v[94:97], v[162:165], v[194:197], v[94:97]
	v_mfma_f32_16x16x32_bf16 v[86:89], v[170:173], v[194:197], v[86:89]
	v_mfma_f32_16x16x32_bf16 v[78:81], v[162:165], v[202:205], v[78:81]
	v_mfma_f32_16x16x32_bf16 v[70:73], v[170:173], v[202:205], v[70:73]
	s_barrier
	s_setprio 0
	s_add_i32 s48, s48, s28
	v_lshl_add_u64 v[206:207], s[2:3], 0, v[132:133]
	s_mov_b32 m0, s48
	ds_read_b128 v[174:177], v141 offset:16384
	ds_read_b128 v[178:181], v141 offset:17408
	ds_read_b128 v[182:185], v141 offset:18432
	ds_read_b128 v[186:189], v141 offset:19456
	ds_read_b128 v[190:193], v141 offset:20480
	ds_read_b128 v[194:197], v141 offset:21504
	ds_read_b128 v[198:201], v141 offset:22528
	ds_read_b128 v[202:205], v141 offset:23552
	global_load_lds_dwordx4 v[206:207], off
	s_add_i32 m0, s48, 0x2000
	s_add_u32 s48, s2, 0x40000
	v_lshl_add_u64 v[218:219], s[2:3], 0, v[130:131]
	s_addc_u32 s49, s3, 0
	s_add_i32 s50, s50, s28
	global_load_lds_dwordx4 v[218:219], off
	v_lshl_add_u64 v[222:223], s[48:49], 0, v[132:133]
	s_mov_b32 m0, s50
	v_lshl_add_u64 v[224:225], s[26:27], 0, v[130:131]
	global_load_lds_dwordx4 v[222:223], off
	v_lshl_add_u64 v[222:223], s[48:49], 0, v[130:131]
	s_add_i32 m0, s50, 0x2000
	s_nop 0
	global_load_lds_dwordx4 v[222:223], off
	v_lshl_add_u64 v[222:223], s[26:27], 0, v[132:133]
	s_mov_b32 m0, s23
	s_nop 0
	global_load_lds_dwordx4 v[222:223], off
	s_mov_b32 m0, s31
	s_nop 0
	global_load_lds_dwordx4 v[224:225], off
	s_waitcnt vmcnt(8)
	s_waitcnt lgkmcnt(0)
	s_setprio 1
	s_barrier
	v_mfma_f32_16x16x32_bf16 v[58:61], v[142:145], v[174:177], v[58:61]
	v_mfma_f32_16x16x32_bf16 v[50:53], v[150:153], v[174:177], v[50:53]
	v_mfma_f32_16x16x32_bf16 v[42:45], v[142:145], v[182:185], v[42:45]
	v_mfma_f32_16x16x32_bf16 v[34:37], v[150:153], v[182:185], v[34:37]
	v_mfma_f32_16x16x32_bf16 v[26:29], v[142:145], v[190:193], v[26:29]
	v_mfma_f32_16x16x32_bf16 v[18:21], v[150:153], v[190:193], v[18:21]
	v_mfma_f32_16x16x32_bf16 v[10:13], v[142:145], v[198:201], v[10:13]
	v_mfma_f32_16x16x32_bf16 v[2:5], v[150:153], v[198:201], v[2:5]
	v_mfma_f32_16x16x32_bf16 v[58:61], v[146:149], v[178:181], v[58:61]
	v_mfma_f32_16x16x32_bf16 v[50:53], v[154:157], v[178:181], v[50:53]
	v_mfma_f32_16x16x32_bf16 v[42:45], v[146:149], v[186:189], v[42:45]
	v_mfma_f32_16x16x32_bf16 v[34:37], v[154:157], v[186:189], v[34:37]
	v_mfma_f32_16x16x32_bf16 v[26:29], v[146:149], v[194:197], v[26:29]
	v_mfma_f32_16x16x32_bf16 v[18:21], v[154:157], v[194:197], v[18:21]
	v_mfma_f32_16x16x32_bf16 v[10:13], v[146:149], v[202:205], v[10:13]
	v_mfma_f32_16x16x32_bf16 v[2:5], v[154:157], v[202:205], v[2:5]
	v_mfma_f32_16x16x32_bf16 v[62:65], v[158:161], v[174:177], v[62:65]
	v_mfma_f32_16x16x32_bf16 v[54:57], v[166:169], v[174:177], v[54:57]
	v_mfma_f32_16x16x32_bf16 v[46:49], v[158:161], v[182:185], v[46:49]
	v_mfma_f32_16x16x32_bf16 v[38:41], v[166:169], v[182:185], v[38:41]
	v_mfma_f32_16x16x32_bf16 v[30:33], v[158:161], v[190:193], v[30:33]
	v_mfma_f32_16x16x32_bf16 v[22:25], v[166:169], v[190:193], v[22:25]
	v_mfma_f32_16x16x32_bf16 v[14:17], v[158:161], v[198:201], v[14:17]
	v_mfma_f32_16x16x32_bf16 v[6:9], v[166:169], v[198:201], v[6:9]
	v_mfma_f32_16x16x32_bf16 v[62:65], v[162:165], v[178:181], v[62:65]
	v_mfma_f32_16x16x32_bf16 v[54:57], v[170:173], v[178:181], v[54:57]
	v_mfma_f32_16x16x32_bf16 v[46:49], v[162:165], v[186:189], v[46:49]
	v_mfma_f32_16x16x32_bf16 v[38:41], v[170:173], v[186:189], v[38:41]
	v_mfma_f32_16x16x32_bf16 v[30:33], v[162:165], v[194:197], v[30:33]
	v_mfma_f32_16x16x32_bf16 v[22:25], v[170:173], v[194:197], v[22:25]
	v_mfma_f32_16x16x32_bf16 v[14:17], v[162:165], v[202:205], v[14:17]
	v_mfma_f32_16x16x32_bf16 v[6:9], v[170:173], v[202:205], v[6:9]
	s_barrier
	s_setprio 0
	s_add_i32 s48, 0, 0x18000
	s_add_i32 s49, 0, 0x1c000
	v_add_u32_e32 v154, s48, v140
	v_add_u32_e32 v170, s49, v140
	ds_read_b128 v[142:145], v154
	ds_read_b128 v[146:149], v154 offset:1024
	ds_read_b128 v[150:153], v154 offset:2048
	ds_read_b128 v[154:157], v154 offset:3072
	ds_read_b128 v[158:161], v170
	ds_read_b128 v[162:165], v170 offset:1024
	ds_read_b128 v[166:169], v170 offset:2048
	ds_read_b128 v[170:173], v170 offset:3072
	s_add_u32 s26, s26, 0x40000
	s_addc_u32 s27, s27, 0
	s_mov_b32 m0, s33
	v_lshl_add_u64 v[226:227], s[26:27], 0, v[132:133]
	ds_read_b128 v[174:177], v141 offset:32768
	ds_read_b128 v[178:181], v141 offset:33792
	ds_read_b128 v[182:185], v141 offset:34816
	ds_read_b128 v[186:189], v141 offset:35840
	ds_read_b128 v[190:193], v141 offset:36864
	ds_read_b128 v[194:197], v141 offset:37888
	ds_read_b128 v[198:201], v141 offset:38912
	ds_read_b128 v[202:205], v141 offset:39936
	global_load_lds_dwordx4 v[226:227], off
	v_lshl_add_u64 v[226:227], s[26:27], 0, v[130:131]
	s_mov_b32 m0, s34
	s_nop 0
	global_load_lds_dwordx4 v[226:227], off
	s_waitcnt vmcnt(8)
	s_waitcnt lgkmcnt(0)
	s_setprio 1
	s_barrier
	v_mfma_f32_16x16x32_bf16 v[122:125], v[142:145], v[174:177], v[122:125]
	v_mfma_f32_16x16x32_bf16 v[114:117], v[150:153], v[174:177], v[114:117]
	v_mfma_f32_16x16x32_bf16 v[106:109], v[142:145], v[182:185], v[106:109]
	v_mfma_f32_16x16x32_bf16 v[98:101], v[150:153], v[182:185], v[98:101]
	v_mfma_f32_16x16x32_bf16 v[90:93], v[142:145], v[190:193], v[90:93]
	v_mfma_f32_16x16x32_bf16 v[82:85], v[150:153], v[190:193], v[82:85]
	v_mfma_f32_16x16x32_bf16 v[74:77], v[142:145], v[198:201], v[74:77]
	v_mfma_f32_16x16x32_bf16 v[66:69], v[150:153], v[198:201], v[66:69]
	v_mfma_f32_16x16x32_bf16 v[122:125], v[146:149], v[178:181], v[122:125]
	v_mfma_f32_16x16x32_bf16 v[114:117], v[154:157], v[178:181], v[114:117]
	v_mfma_f32_16x16x32_bf16 v[106:109], v[146:149], v[186:189], v[106:109]
	v_mfma_f32_16x16x32_bf16 v[98:101], v[154:157], v[186:189], v[98:101]
	v_mfma_f32_16x16x32_bf16 v[90:93], v[146:149], v[194:197], v[90:93]
	v_mfma_f32_16x16x32_bf16 v[82:85], v[154:157], v[194:197], v[82:85]
	v_mfma_f32_16x16x32_bf16 v[74:77], v[146:149], v[202:205], v[74:77]
	v_mfma_f32_16x16x32_bf16 v[66:69], v[154:157], v[202:205], v[66:69]
	v_mfma_f32_16x16x32_bf16 v[126:129], v[158:161], v[174:177], v[126:129]
	v_mfma_f32_16x16x32_bf16 v[118:121], v[166:169], v[174:177], v[118:121]
	v_mfma_f32_16x16x32_bf16 v[110:113], v[158:161], v[182:185], v[110:113]
	v_mfma_f32_16x16x32_bf16 v[102:105], v[166:169], v[182:185], v[102:105]
	v_mfma_f32_16x16x32_bf16 v[94:97], v[158:161], v[190:193], v[94:97]
	v_mfma_f32_16x16x32_bf16 v[86:89], v[166:169], v[190:193], v[86:89]
	v_mfma_f32_16x16x32_bf16 v[78:81], v[158:161], v[198:201], v[78:81]
	v_mfma_f32_16x16x32_bf16 v[70:73], v[166:169], v[198:201], v[70:73]
	v_mfma_f32_16x16x32_bf16 v[126:129], v[162:165], v[178:181], v[126:129]
	v_mfma_f32_16x16x32_bf16 v[118:121], v[170:173], v[178:181], v[118:121]
	v_mfma_f32_16x16x32_bf16 v[110:113], v[162:165], v[186:189], v[110:113]
	v_mfma_f32_16x16x32_bf16 v[102:105], v[170:173], v[186:189], v[102:105]
	v_mfma_f32_16x16x32_bf16 v[94:97], v[162:165], v[194:197], v[94:97]
	v_mfma_f32_16x16x32_bf16 v[86:89], v[170:173], v[194:197], v[86:89]
	v_mfma_f32_16x16x32_bf16 v[78:81], v[162:165], v[202:205], v[78:81]
	v_mfma_f32_16x16x32_bf16 v[70:73], v[170:173], v[202:205], v[70:73]
	s_barrier
	s_setprio 0
	s_add_i32 s26, s48, s28
	v_lshl_add_u64 v[206:207], v[206:207], 0, s[44:45]
	s_mov_b32 m0, s26
	ds_read_b128 v[174:177], v141 offset:49152
	ds_read_b128 v[178:181], v141 offset:50176
	ds_read_b128 v[182:185], v141 offset:51200
	ds_read_b128 v[186:189], v141 offset:52224
	ds_read_b128 v[190:193], v141 offset:53248
	ds_read_b128 v[194:197], v141 offset:54272
	ds_read_b128 v[198:201], v141 offset:55296
	ds_read_b128 v[202:205], v141 offset:56320
	global_load_lds_dwordx4 v[206:207], off
	s_add_i32 m0, s26, 0x2000
	s_add_u32 s2, s2, 0x40080
	v_lshl_add_u64 v[206:207], v[218:219], 0, s[44:45]
	s_addc_u32 s3, s3, 0
	s_add_i32 s26, s49, s28
	global_load_lds_dwordx4 v[206:207], off
	v_lshl_add_u64 v[206:207], s[2:3], 0, v[132:133]
	s_mov_b32 m0, s26
	s_nop 0
	global_load_lds_dwordx4 v[206:207], off
	v_lshl_add_u64 v[206:207], s[2:3], 0, v[130:131]
	s_add_i32 m0, s26, 0x2000
	s_nop 0
	global_load_lds_dwordx4 v[206:207], off
	v_lshl_add_u64 v[206:207], v[222:223], 0, s[44:45]
	s_mov_b32 m0, s35
	s_nop 0
	global_load_lds_dwordx4 v[206:207], off
	v_lshl_add_u64 v[206:207], v[224:225], 0, s[44:45]
	s_mov_b32 m0, s36
	s_nop 0
	global_load_lds_dwordx4 v[206:207], off
	s_waitcnt vmcnt(8)
	s_waitcnt lgkmcnt(0)
	s_setprio 1
	s_barrier
	v_mfma_f32_16x16x32_bf16 v[58:61], v[142:145], v[174:177], v[58:61]
	v_mfma_f32_16x16x32_bf16 v[50:53], v[150:153], v[174:177], v[50:53]
	v_mfma_f32_16x16x32_bf16 v[42:45], v[142:145], v[182:185], v[42:45]
	v_mfma_f32_16x16x32_bf16 v[34:37], v[150:153], v[182:185], v[34:37]
	v_mfma_f32_16x16x32_bf16 v[26:29], v[142:145], v[190:193], v[26:29]
	v_mfma_f32_16x16x32_bf16 v[18:21], v[150:153], v[190:193], v[18:21]
	v_mfma_f32_16x16x32_bf16 v[10:13], v[142:145], v[198:201], v[10:13]
	v_mfma_f32_16x16x32_bf16 v[2:5], v[150:153], v[198:201], v[2:5]
	v_mfma_f32_16x16x32_bf16 v[58:61], v[146:149], v[178:181], v[58:61]
	v_mfma_f32_16x16x32_bf16 v[50:53], v[154:157], v[178:181], v[50:53]
	v_mfma_f32_16x16x32_bf16 v[42:45], v[146:149], v[186:189], v[42:45]
	v_mfma_f32_16x16x32_bf16 v[34:37], v[154:157], v[186:189], v[34:37]
	v_mfma_f32_16x16x32_bf16 v[26:29], v[146:149], v[194:197], v[26:29]
	v_mfma_f32_16x16x32_bf16 v[18:21], v[154:157], v[194:197], v[18:21]
	v_mfma_f32_16x16x32_bf16 v[10:13], v[146:149], v[202:205], v[10:13]
	v_mfma_f32_16x16x32_bf16 v[2:5], v[154:157], v[202:205], v[2:5]
	v_mfma_f32_16x16x32_bf16 v[62:65], v[158:161], v[174:177], v[62:65]
	v_mfma_f32_16x16x32_bf16 v[54:57], v[166:169], v[174:177], v[54:57]
	v_mfma_f32_16x16x32_bf16 v[46:49], v[158:161], v[182:185], v[46:49]
	v_mfma_f32_16x16x32_bf16 v[38:41], v[166:169], v[182:185], v[38:41]
	v_mfma_f32_16x16x32_bf16 v[30:33], v[158:161], v[190:193], v[30:33]
	v_mfma_f32_16x16x32_bf16 v[22:25], v[166:169], v[190:193], v[22:25]
	v_mfma_f32_16x16x32_bf16 v[14:17], v[158:161], v[198:201], v[14:17]
	v_mfma_f32_16x16x32_bf16 v[6:9], v[166:169], v[198:201], v[6:9]
	v_mfma_f32_16x16x32_bf16 v[62:65], v[162:165], v[178:181], v[62:65]
	v_mfma_f32_16x16x32_bf16 v[54:57], v[170:173], v[178:181], v[54:57]
	v_mfma_f32_16x16x32_bf16 v[46:49], v[162:165], v[186:189], v[46:49]
	v_mfma_f32_16x16x32_bf16 v[38:41], v[170:173], v[186:189], v[38:41]
	v_mfma_f32_16x16x32_bf16 v[30:33], v[162:165], v[194:197], v[30:33]
	v_mfma_f32_16x16x32_bf16 v[22:25], v[170:173], v[194:197], v[22:25]
	v_mfma_f32_16x16x32_bf16 v[14:17], v[162:165], v[202:205], v[14:17]
	v_mfma_f32_16x16x32_bf16 v[6:9], v[170:173], v[202:205], v[6:9]
	s_barrier
	s_setprio 0
	s_add_i32 s47, s47, 2
	s_add_u32 s4, s4, 0x100
	s_addc_u32 s5, s5, 0
	s_add_u32 s42, s42, 0x100
	s_addc_u32 s46, s46, 0
	s_cmp_gt_u32 s47, 13
	s_cbranch_scc0 .LBB0_783
	s_and_b64 vcc, exec, s[12:13]
	s_cbranch_vccz .LBB0_786
	s_barrier

.LBB0_849:
	s_add_u32 s2, s18, 0x100
	s_addc_u32 s3, s19, 0
	s_add_i32 s47, 0, 0x10000
	s_cmp_eq_u32 s46, 40
	s_cselect_b32 s23, s9, s3
	s_cselect_b32 s22, s8, s2
	v_add_u32_e32 v0, s47, v135
	s_cselect_b32 s21, s15, s42
	s_cselect_b32 s20, s14, s17
	s_add_i32 s48, 0, 0x14000
	ds_read_b128 v[146:149], v0
	ds_read_b128 v[150:153], v0 offset:1024
	ds_read_b128 v[154:157], v0 offset:2048
	ds_read_b128 v[158:161], v0 offset:3072
	v_add_u32_e32 v0, s48, v135
	ds_read_b128 v[162:165], v0
	ds_read_b128 v[166:169], v0 offset:1024
	ds_read_b128 v[170:173], v0 offset:2048
	ds_read_b128 v[174:177], v0 offset:3072
	v_lshl_add_u64 v[142:143], s[18:19], 0, v[138:139]
	s_add_i32 m0, s25, 0xc000
	ds_read_b128 v[178:181], v144
	ds_read_b128 v[182:185], v144 offset:1024
	ds_read_b128 v[186:189], v144 offset:2048
	ds_read_b128 v[190:193], v144 offset:3072
	ds_read_b128 v[194:197], v144 offset:4096
	ds_read_b128 v[198:201], v144 offset:5120
	ds_read_b128 v[202:205], v144 offset:6144
	ds_read_b128 v[222:225], v144 offset:7168
	global_load_lds_dwordx4 v[142:143], off
	v_lshl_add_u64 v[142:143], s[18:19], 0, v[140:141]
	s_add_i32 m0, s25, 0xe000
	s_nop 0
	global_load_lds_dwordx4 v[142:143], off
	s_waitcnt vmcnt(8)
	s_waitcnt lgkmcnt(0)
	s_setprio 1
	s_barrier
	v_mfma_f32_16x16x32_bf16 v[126:129], v[146:149], v[178:181], v[126:129]
	v_mfma_f32_16x16x32_bf16 v[122:125], v[154:157], v[178:181], v[122:125]
	v_mfma_f32_16x16x32_bf16 v[110:113], v[146:149], v[186:189], v[110:113]
	v_mfma_f32_16x16x32_bf16 v[106:109], v[154:157], v[186:189], v[106:109]
	v_mfma_f32_16x16x32_bf16 v[94:97], v[146:149], v[194:197], v[94:97]
	v_mfma_f32_16x16x32_bf16 v[90:93], v[154:157], v[194:197], v[90:93]
	v_mfma_f32_16x16x32_bf16 v[78:81], v[146:149], v[202:205], v[78:81]
	v_mfma_f32_16x16x32_bf16 v[74:77], v[154:157], v[202:205], v[74:77]
	v_mfma_f32_16x16x32_bf16 v[126:129], v[150:153], v[182:185], v[126:129]
	v_mfma_f32_16x16x32_bf16 v[122:125], v[158:161], v[182:185], v[122:125]
	v_mfma_f32_16x16x32_bf16 v[110:113], v[150:153], v[190:193], v[110:113]
	v_mfma_f32_16x16x32_bf16 v[106:109], v[158:161], v[190:193], v[106:109]
	v_mfma_f32_16x16x32_bf16 v[94:97], v[150:153], v[198:201], v[94:97]
	v_mfma_f32_16x16x32_bf16 v[90:93], v[158:161], v[198:201], v[90:93]
	v_mfma_f32_16x16x32_bf16 v[78:81], v[150:153], v[222:225], v[78:81]
	v_mfma_f32_16x16x32_bf16 v[74:77], v[158:161], v[222:225], v[74:77]
	v_mfma_f32_16x16x32_bf16 v[118:121], v[162:165], v[178:181], v[118:121]
	v_mfma_f32_16x16x32_bf16 v[114:117], v[170:173], v[178:181], v[114:117]
	v_mfma_f32_16x16x32_bf16 v[102:105], v[162:165], v[186:189], v[102:105]
	v_mfma_f32_16x16x32_bf16 v[98:101], v[170:173], v[186:189], v[98:101]
	v_mfma_f32_16x16x32_bf16 v[86:89], v[162:165], v[194:197], v[86:89]
	v_mfma_f32_16x16x32_bf16 v[82:85], v[170:173], v[194:197], v[82:85]
	v_mfma_f32_16x16x32_bf16 v[70:73], v[162:165], v[202:205], v[70:73]
	v_mfma_f32_16x16x32_bf16 v[66:69], v[170:173], v[202:205], v[66:69]
	v_mfma_f32_16x16x32_bf16 v[118:121], v[166:169], v[182:185], v[118:121]
	v_mfma_f32_16x16x32_bf16 v[114:117], v[174:177], v[182:185], v[114:117]
	v_mfma_f32_16x16x32_bf16 v[102:105], v[166:169], v[190:193], v[102:105]
	v_mfma_f32_16x16x32_bf16 v[98:101], v[174:177], v[190:193], v[98:101]
	v_mfma_f32_16x16x32_bf16 v[86:89], v[166:169], v[198:201], v[86:89]
	v_mfma_f32_16x16x32_bf16 v[82:85], v[174:177], v[198:201], v[82:85]
	v_mfma_f32_16x16x32_bf16 v[70:73], v[166:169], v[222:225], v[70:73]
	v_mfma_f32_16x16x32_bf16 v[66:69], v[174:177], v[222:225], v[66:69]
	s_barrier
	s_setprio 0
	s_add_i32 s18, s47, s24
	v_lshl_add_u64 v[142:143], s[20:21], 0, v[130:131]
	s_mov_b32 m0, s18
	ds_read_b128 v[178:181], v144 offset:16384
	ds_read_b128 v[182:185], v144 offset:17408
	ds_read_b128 v[186:189], v144 offset:18432
	ds_read_b128 v[190:193], v144 offset:19456
	ds_read_b128 v[194:197], v144 offset:20480
	ds_read_b128 v[198:201], v144 offset:21504
	ds_read_b128 v[202:205], v144 offset:22528
	ds_read_b128 v[222:225], v144 offset:23552
	global_load_lds_dwordx4 v[142:143], off
	s_add_i32 m0, s18, 0x2000
	s_add_u32 s18, s20, 0xb0000
	v_lshl_add_u64 v[206:207], s[20:21], 0, v[132:133]
	s_addc_u32 s19, s21, 0
	s_add_i32 s47, s48, s24
	global_load_lds_dwordx4 v[206:207], off
	v_lshl_add_u64 v[218:219], s[18:19], 0, v[130:131]
	s_mov_b32 m0, s47
	v_lshl_add_u64 v[226:227], s[22:23], 0, v[132:133]
	global_load_lds_dwordx4 v[218:219], off
	v_lshl_add_u64 v[218:219], s[18:19], 0, v[132:133]
	s_add_i32 m0, s47, 0x2000
	s_nop 0
	global_load_lds_dwordx4 v[218:219], off
	v_lshl_add_u64 v[218:219], s[22:23], 0, v[130:131]
	s_mov_b32 m0, s25
	s_nop 0
	global_load_lds_dwordx4 v[218:219], off
	s_mov_b32 m0, s26
	s_nop 0
	global_load_lds_dwordx4 v[226:227], off
	s_waitcnt vmcnt(8)
	s_waitcnt lgkmcnt(0)
	s_setprio 1
	s_barrier
	v_mfma_f32_16x16x32_bf16 v[62:65], v[146:149], v[178:181], v[62:65]
	v_mfma_f32_16x16x32_bf16 v[58:61], v[154:157], v[178:181], v[58:61]
	v_mfma_f32_16x16x32_bf16 v[46:49], v[146:149], v[186:189], v[46:49]
	v_mfma_f32_16x16x32_bf16 v[42:45], v[154:157], v[186:189], v[42:45]
	v_mfma_f32_16x16x32_bf16 v[30:33], v[146:149], v[194:197], v[30:33]
	v_mfma_f32_16x16x32_bf16 v[26:29], v[154:157], v[194:197], v[26:29]
	v_mfma_f32_16x16x32_bf16 v[14:17], v[146:149], v[202:205], v[14:17]
	v_mfma_f32_16x16x32_bf16 v[10:13], v[154:157], v[202:205], v[10:13]
	v_mfma_f32_16x16x32_bf16 v[62:65], v[150:153], v[182:185], v[62:65]
	v_mfma_f32_16x16x32_bf16 v[58:61], v[158:161], v[182:185], v[58:61]
	v_mfma_f32_16x16x32_bf16 v[46:49], v[150:153], v[190:193], v[46:49]
	v_mfma_f32_16x16x32_bf16 v[42:45], v[158:161], v[190:193], v[42:45]
	v_mfma_f32_16x16x32_bf16 v[30:33], v[150:153], v[198:201], v[30:33]
	v_mfma_f32_16x16x32_bf16 v[26:29], v[158:161], v[198:201], v[26:29]
	v_mfma_f32_16x16x32_bf16 v[14:17], v[150:153], v[222:225], v[14:17]
	v_mfma_f32_16x16x32_bf16 v[10:13], v[158:161], v[222:225], v[10:13]
	v_mfma_f32_16x16x32_bf16 v[54:57], v[162:165], v[178:181], v[54:57]
	v_mfma_f32_16x16x32_bf16 v[50:53], v[170:173], v[178:181], v[50:53]
	v_mfma_f32_16x16x32_bf16 v[38:41], v[162:165], v[186:189], v[38:41]
	v_mfma_f32_16x16x32_bf16 v[34:37], v[170:173], v[186:189], v[34:37]
	v_mfma_f32_16x16x32_bf16 v[22:25], v[162:165], v[194:197], v[22:25]
	v_mfma_f32_16x16x32_bf16 v[18:21], v[170:173], v[194:197], v[18:21]
	v_mfma_f32_16x16x32_bf16 v[6:9], v[162:165], v[202:205], v[6:9]
	v_mfma_f32_16x16x32_bf16 v[2:5], v[170:173], v[202:205], v[2:5]
	v_mfma_f32_16x16x32_bf16 v[54:57], v[166:169], v[182:185], v[54:57]
	v_mfma_f32_16x16x32_bf16 v[50:53], v[174:177], v[182:185], v[50:53]
	v_mfma_f32_16x16x32_bf16 v[38:41], v[166:169], v[190:193], v[38:41]
	v_mfma_f32_16x16x32_bf16 v[34:37], v[174:177], v[190:193], v[34:37]
	v_mfma_f32_16x16x32_bf16 v[22:25], v[166:169], v[198:201], v[22:25]
	v_mfma_f32_16x16x32_bf16 v[18:21], v[174:177], v[198:201], v[18:21]
	v_mfma_f32_16x16x32_bf16 v[6:9], v[166:169], v[222:225], v[6:9]
	v_mfma_f32_16x16x32_bf16 v[2:5], v[174:177], v[222:225], v[2:5]
	s_barrier
	s_setprio 0
	s_add_i32 s47, 0, 0x18000
	v_add_u32_e32 v0, s47, v135
	s_add_i32 s48, 0, 0x1c000
	ds_read_b128 v[146:149], v0
	ds_read_b128 v[150:153], v0 offset:1024
	ds_read_b128 v[154:157], v0 offset:2048
	ds_read_b128 v[158:161], v0 offset:3072
	v_add_u32_e32 v0, s48, v135
	ds_read_b128 v[162:165], v0
	ds_read_b128 v[166:169], v0 offset:1024
	ds_read_b128 v[170:173], v0 offset:2048
	ds_read_b128 v[174:177], v0 offset:3072
	s_add_u32 s18, s22, 0xb0000
	s_addc_u32 s19, s23, 0
	s_mov_b32 m0, s27
	v_lshl_add_u64 v[228:229], s[18:19], 0, v[130:131]
	ds_read_b128 v[178:181], v144 offset:32768
	ds_read_b128 v[182:185], v144 offset:33792
	ds_read_b128 v[186:189], v144 offset:34816
	ds_read_b128 v[190:193], v144 offset:35840
	ds_read_b128 v[194:197], v144 offset:36864
	ds_read_b128 v[198:201], v144 offset:37888
	ds_read_b128 v[202:205], v144 offset:38912
	ds_read_b128 v[222:225], v144 offset:39936
	global_load_lds_dwordx4 v[228:229], off
	v_lshl_add_u64 v[228:229], s[18:19], 0, v[132:133]
	s_mov_b32 m0, s28
	s_nop 0
	global_load_lds_dwordx4 v[228:229], off
	s_waitcnt vmcnt(8)
	s_waitcnt lgkmcnt(0)
	s_setprio 1
	s_barrier
	v_mfma_f32_16x16x32_bf16 v[126:129], v[146:149], v[178:181], v[126:129]
	v_mfma_f32_16x16x32_bf16 v[122:125], v[154:157], v[178:181], v[122:125]
	v_mfma_f32_16x16x32_bf16 v[110:113], v[146:149], v[186:189], v[110:113]
	v_mfma_f32_16x16x32_bf16 v[106:109], v[154:157], v[186:189], v[106:109]
	v_mfma_f32_16x16x32_bf16 v[94:97], v[146:149], v[194:197], v[94:97]
	v_mfma_f32_16x16x32_bf16 v[90:93], v[154:157], v[194:197], v[90:93]
	v_mfma_f32_16x16x32_bf16 v[78:81], v[146:149], v[202:205], v[78:81]
	v_mfma_f32_16x16x32_bf16 v[74:77], v[154:157], v[202:205], v[74:77]
	v_mfma_f32_16x16x32_bf16 v[126:129], v[150:153], v[182:185], v[126:129]
	v_mfma_f32_16x16x32_bf16 v[122:125], v[158:161], v[182:185], v[122:125]
	v_mfma_f32_16x16x32_bf16 v[110:113], v[150:153], v[190:193], v[110:113]
	v_mfma_f32_16x16x32_bf16 v[106:109], v[158:161], v[190:193], v[106:109]
	v_mfma_f32_16x16x32_bf16 v[94:97], v[150:153], v[198:201], v[94:97]
	v_mfma_f32_16x16x32_bf16 v[90:93], v[158:161], v[198:201], v[90:93]
	v_mfma_f32_16x16x32_bf16 v[78:81], v[150:153], v[222:225], v[78:81]
	v_mfma_f32_16x16x32_bf16 v[74:77], v[158:161], v[222:225], v[74:77]
	v_mfma_f32_16x16x32_bf16 v[118:121], v[162:165], v[178:181], v[118:121]
	v_mfma_f32_16x16x32_bf16 v[114:117], v[170:173], v[178:181], v[114:117]
	v_mfma_f32_16x16x32_bf16 v[102:105], v[162:165], v[186:189], v[102:105]
	v_mfma_f32_16x16x32_bf16 v[98:101], v[170:173], v[186:189], v[98:101]
	v_mfma_f32_16x16x32_bf16 v[86:89], v[162:165], v[194:197], v[86:89]
	v_mfma_f32_16x16x32_bf16 v[82:85], v[170:173], v[194:197], v[82:85]
	v_mfma_f32_16x16x32_bf16 v[70:73], v[162:165], v[202:205], v[70:73]
	v_mfma_f32_16x16x32_bf16 v[66:69], v[170:173], v[202:205], v[66:69]
	v_mfma_f32_16x16x32_bf16 v[118:121], v[166:169], v[182:185], v[118:121]
	v_mfma_f32_16x16x32_bf16 v[114:117], v[174:177], v[182:185], v[114:117]
	v_mfma_f32_16x16x32_bf16 v[102:105], v[166:169], v[190:193], v[102:105]
	v_mfma_f32_16x16x32_bf16 v[98:101], v[174:177], v[190:193], v[98:101]
	v_mfma_f32_16x16x32_bf16 v[86:89], v[166:169], v[198:201], v[86:89]
	v_mfma_f32_16x16x32_bf16 v[82:85], v[174:177], v[198:201], v[82:85]
	v_mfma_f32_16x16x32_bf16 v[70:73], v[166:169], v[222:225], v[70:73]
	v_mfma_f32_16x16x32_bf16 v[66:69], v[174:177], v[222:225], v[66:69]
	s_barrier
	s_setprio 0
	s_add_i32 s18, s47, s24
	v_lshl_add_u64 v[142:143], v[142:143], 0, s[44:45]
	s_mov_b32 m0, s18
	ds_read_b128 v[178:181], v144 offset:49152
	ds_read_b128 v[182:185], v144 offset:50176
	ds_read_b128 v[186:189], v144 offset:51200
	ds_read_b128 v[190:193], v144 offset:52224
	ds_read_b128 v[194:197], v144 offset:53248
	ds_read_b128 v[198:201], v144 offset:54272
	ds_read_b128 v[202:205], v144 offset:55296
	ds_read_b128 v[222:225], v144 offset:56320
	global_load_lds_dwordx4 v[142:143], off
	s_add_i32 m0, s18, 0x2000
	s_add_u32 s18, s20, 0xb0080
	v_lshl_add_u64 v[142:143], v[206:207], 0, s[44:45]
	s_addc_u32 s19, s21, 0
	s_add_i32 s20, s48, s24
	global_load_lds_dwordx4 v[142:143], off
	v_lshl_add_u64 v[142:143], s[18:19], 0, v[130:131]
	s_mov_b32 m0, s20
	s_nop 0
	global_load_lds_dwordx4 v[142:143], off
	v_lshl_add_u64 v[142:143], s[18:19], 0, v[132:133]
	s_add_i32 m0, s20, 0x2000
	s_nop 0
	global_load_lds_dwordx4 v[142:143], off
	v_lshl_add_u64 v[142:143], v[218:219], 0, s[44:45]
	s_mov_b32 m0, s31
	s_nop 0
	global_load_lds_dwordx4 v[142:143], off
	v_lshl_add_u64 v[142:143], v[226:227], 0, s[44:45]
	s_mov_b32 m0, s33
	s_nop 0
	global_load_lds_dwordx4 v[142:143], off
	s_waitcnt vmcnt(8)
	s_waitcnt lgkmcnt(0)
	s_setprio 1
	s_barrier
	v_mfma_f32_16x16x32_bf16 v[62:65], v[146:149], v[178:181], v[62:65]
	v_mfma_f32_16x16x32_bf16 v[58:61], v[154:157], v[178:181], v[58:61]
	v_mfma_f32_16x16x32_bf16 v[46:49], v[146:149], v[186:189], v[46:49]
	v_mfma_f32_16x16x32_bf16 v[42:45], v[154:157], v[186:189], v[42:45]
	v_mfma_f32_16x16x32_bf16 v[30:33], v[146:149], v[194:197], v[30:33]
	v_mfma_f32_16x16x32_bf16 v[26:29], v[154:157], v[194:197], v[26:29]
	v_mfma_f32_16x16x32_bf16 v[14:17], v[146:149], v[202:205], v[14:17]
	v_mfma_f32_16x16x32_bf16 v[10:13], v[154:157], v[202:205], v[10:13]
	v_mfma_f32_16x16x32_bf16 v[62:65], v[150:153], v[182:185], v[62:65]
	v_mfma_f32_16x16x32_bf16 v[58:61], v[158:161], v[182:185], v[58:61]
	v_mfma_f32_16x16x32_bf16 v[46:49], v[150:153], v[190:193], v[46:49]
	v_mfma_f32_16x16x32_bf16 v[42:45], v[158:161], v[190:193], v[42:45]
	v_mfma_f32_16x16x32_bf16 v[30:33], v[150:153], v[198:201], v[30:33]
	v_mfma_f32_16x16x32_bf16 v[26:29], v[158:161], v[198:201], v[26:29]
	v_mfma_f32_16x16x32_bf16 v[14:17], v[150:153], v[222:225], v[14:17]
	v_mfma_f32_16x16x32_bf16 v[10:13], v[158:161], v[222:225], v[10:13]
	v_mfma_f32_16x16x32_bf16 v[54:57], v[162:165], v[178:181], v[54:57]
	v_mfma_f32_16x16x32_bf16 v[50:53], v[170:173], v[178:181], v[50:53]
	v_mfma_f32_16x16x32_bf16 v[38:41], v[162:165], v[186:189], v[38:41]
	v_mfma_f32_16x16x32_bf16 v[34:37], v[170:173], v[186:189], v[34:37]
	v_mfma_f32_16x16x32_bf16 v[22:25], v[162:165], v[194:197], v[22:25]
	v_mfma_f32_16x16x32_bf16 v[18:21], v[170:173], v[194:197], v[18:21]
	v_mfma_f32_16x16x32_bf16 v[6:9], v[162:165], v[202:205], v[6:9]
	v_mfma_f32_16x16x32_bf16 v[2:5], v[170:173], v[202:205], v[2:5]
	v_mfma_f32_16x16x32_bf16 v[54:57], v[166:169], v[182:185], v[54:57]
	v_mfma_f32_16x16x32_bf16 v[50:53], v[174:177], v[182:185], v[50:53]
	v_mfma_f32_16x16x32_bf16 v[38:41], v[166:169], v[190:193], v[38:41]
	v_mfma_f32_16x16x32_bf16 v[34:37], v[174:177], v[190:193], v[34:37]
	v_mfma_f32_16x16x32_bf16 v[22:25], v[166:169], v[198:201], v[22:25]
	v_mfma_f32_16x16x32_bf16 v[18:21], v[174:177], v[198:201], v[18:21]
	v_mfma_f32_16x16x32_bf16 v[6:9], v[166:169], v[222:225], v[6:9]
	v_mfma_f32_16x16x32_bf16 v[2:5], v[174:177], v[222:225], v[2:5]
	s_barrier
	s_setprio 0
	s_add_i32 s46, s46, 2
	s_add_u32 s17, s17, 0x100
	s_addc_u32 s42, s42, 0
	s_cmp_gt_u32 s46, 41
	s_mov_b64 s[18:19], s[2:3]
	s_cbranch_scc0 .LBB0_849
	s_and_b64 vcc, exec, s[12:13]
	s_cbranch_vccz .LBB0_852
	s_barrier
